# v11 with sc1 nt (instead of nt) on the rw2 loader LDS-DMA record loads
# baseline (speedup 1.0000x reference)
; #define GAS __attribute__((address_space(1)))
; __device__ __forceinline__ void rw2_phase(const Ctx& c0) { const Ctx c = fresh(c0);
;     ...
;         const GAS char* gsrc = (j == 0) ? (const GAS char*)(ws + WS_AF) + (size_t)h * 128 * 8192 : (j == 1) ? (const GAS char*)(ws + WS_BF) + (size_t)h * 128 * 8192 : (j == 2) ? (const GAS char*)(ws + WS_VK2F) + (size_t)h * 128 * 8192 : (const GAS char*)(ws + WS_PL) + (size_t)h * 128 * 1024;
;         gsrc += lane * 16;
;     ...
;         RW2_ISSUE(0); RW2_ISSUE(1); RW2_ISSUE(2); RW2_ISSUE(3);
.LBB0_2436:
	s_ashr_i32 s1, s0, 31
	s_add_u32 s7, s2, s8
	s_addc_u32 s12, s3, s9
	s_lshl_b64 s[10:11], s[0:1], s6
	s_add_u32 s0, s7, s10
	s_addc_u32 s1, s12, s11
	v_ashrrev_i32_e32 v83, 31, v82
	v_lshl_add_u64 v[2:3], s[0:1], 0, v[82:83]
	s_mov_b64 s[12:13], 0x400
	v_lshl_add_u64 v[8:9], v[2:3], 0, s[12:13]
	s_mov_b64 s[12:13], 0x800
	s_cmp_lg_u32 s5, 3
	v_lshl_add_u64 v[6:7], v[2:3], 0, s[12:13]
	s_mov_b64 s[12:13], 0xc00
	s_mov_b64 s[0:1], -1
	s_cselect_b64 s[6:7], -1, 0
	s_cmp_eq_u32 s5, 3
	v_lshl_add_u64 v[4:5], v[2:3], 0, s[12:13]
	s_cbranch_scc1 .LBB0_2438
	s_lshl_b32 s12, s5, 13
	s_or_b32 m0, s12, 0x400
	s_mov_b64 s[0:1], 0x1000
	global_load_lds_dwordx4 v[2:3], off sc1 nt
	s_or_b32 m0, s12, 0x800
	v_lshl_add_u64 v[10:11], v[2:3], 0, s[0:1]
	global_load_lds_dwordx4 v[8:9], off sc1 nt
	s_or_b32 m0, s12, 0xc00
	s_mov_b64 s[0:1], 0x1400
	global_load_lds_dwordx4 v[6:7], off sc1 nt
	s_or_b32 m0, s12, 0x1000
	s_nop 0
	global_load_lds_dwordx4 v[4:5], off sc1 nt
	s_or_b32 m0, s12, 0x1400
	s_nop 0
	global_load_lds_dwordx4 v[10:11], off sc1 nt
	v_lshl_add_u64 v[10:11], v[2:3], 0, s[0:1]
	s_or_b32 m0, s12, 0x1800
	s_mov_b64 s[0:1], 0x1800
	global_load_lds_dwordx4 v[10:11], off sc1 nt
	v_lshl_add_u64 v[10:11], v[2:3], 0, s[0:1]
	s_or_b32 m0, s12, 0x1c00
	s_mov_b64 s[0:1], 0x1c00
	global_load_lds_dwordx4 v[10:11], off sc1 nt
	v_lshl_add_u64 v[10:11], v[2:3], 0, s[0:1]
	s_add_i32 m0, s12, 0x2000
	s_mov_b64 s[0:1], 0
	global_load_lds_dwordx4 v[10:11], off sc1 nt
.LBB0_2438:
	s_andn2_b64 vcc, exec, s[0:1]
	s_cbranch_vccnz .LBB0_2440
	s_movk_i32 m0, 0x6400
	s_nop 0
	global_load_lds_dwordx4 v[2:3], off sc1 nt
.LBB0_2440:
	v_cndmask_b32_e64 v0, 0, 1, s[6:7]
	v_cmp_ne_u32_e64 s[0:1], 1, v0
	s_andn2_b64 vcc, exec, s[6:7]
	s_mov_b64 s[12:13], -1
	s_cbranch_vccnz .LBB0_2448
	s_mov_b64 s[12:13], 0x2000
	s_lshl_b32 s14, s5, 13
	v_lshl_add_u64 v[10:11], v[2:3], 0, s[12:13]
	s_add_i32 m0, s14, 0x6800
	s_mov_b64 s[12:13], 0x2400
	global_load_lds_dwordx4 v[10:11], off sc1 nt
	v_lshl_add_u64 v[10:11], v[2:3], 0, s[12:13]
	s_add_i32 m0, s14, 0x6c00
	s_mov_b64 s[12:13], 0x2800
	global_load_lds_dwordx4 v[10:11], off sc1 nt
	v_lshl_add_u64 v[10:11], v[2:3], 0, s[12:13]
	s_add_i32 m0, s14, 0x7000
	s_mov_b64 s[12:13], 0x2c00
	global_load_lds_dwordx4 v[10:11], off sc1 nt
	v_lshl_add_u64 v[10:11], v[2:3], 0, s[12:13]
	s_add_i32 m0, s14, 0x7400
	s_mov_b64 s[12:13], 0x3000
	global_load_lds_dwordx4 v[10:11], off sc1 nt
	v_lshl_add_u64 v[10:11], v[2:3], 0, s[12:13]
	s_add_i32 m0, s14, 0x7800
	s_mov_b64 s[12:13], 0x3400
	global_load_lds_dwordx4 v[10:11], off sc1 nt
	v_lshl_add_u64 v[10:11], v[2:3], 0, s[12:13]
	s_add_i32 m0, s14, 0x7c00
	s_mov_b64 s[12:13], 0x3800
	global_load_lds_dwordx4 v[10:11], off sc1 nt
	v_lshl_add_u64 v[10:11], v[2:3], 0, s[12:13]
	s_or_b32 m0, s14, 0x8000
	s_mov_b64 s[12:13], 0x3c00
	global_load_lds_dwordx4 v[10:11], off sc1 nt
	v_lshl_add_u64 v[10:11], v[2:3], 0, s[12:13]
	s_or_b32 m0, s14, 0x8400
	s_nop 0
	global_load_lds_dwordx4 v[10:11], off sc1 nt
	s_cbranch_execz .LBB0_2449

; __device__ __forceinline__ void rw2_phase(const Ctx& c0) { const Ctx c = fresh(c0);
;     ...
;         RW2_ISSUE(0); RW2_ISSUE(1); RW2_ISSUE(2); RW2_ISSUE(3);
.LBB0_2443:
	s_mov_b64 s[12:13], 0x4000
	s_lshl_b32 s14, s5, 13
	v_lshl_add_u64 v[8:9], v[2:3], 0, s[12:13]
	s_add_i32 m0, s14, 0xcc00
	s_mov_b64 s[12:13], 0x4400
	global_load_lds_dwordx4 v[8:9], off sc1 nt
	v_lshl_add_u64 v[8:9], v[2:3], 0, s[12:13]
	s_add_i32 m0, s14, 0xd000
	s_mov_b64 s[12:13], 0x4800
	global_load_lds_dwordx4 v[8:9], off sc1 nt
	v_lshl_add_u64 v[8:9], v[2:3], 0, s[12:13]
	s_add_i32 m0, s14, 0xd400
	s_mov_b64 s[12:13], 0x4c00
	global_load_lds_dwordx4 v[8:9], off sc1 nt
	v_lshl_add_u64 v[8:9], v[2:3], 0, s[12:13]
	s_add_i32 m0, s14, 0xd800
	s_mov_b64 s[12:13], 0x5000
	global_load_lds_dwordx4 v[8:9], off sc1 nt
	v_lshl_add_u64 v[8:9], v[2:3], 0, s[12:13]
	s_add_i32 m0, s14, 0xdc00
	s_mov_b64 s[12:13], 0x5400
	global_load_lds_dwordx4 v[8:9], off sc1 nt
	v_lshl_add_u64 v[8:9], v[2:3], 0, s[12:13]
	s_add_i32 m0, s14, 0xe000
	s_mov_b64 s[12:13], 0x5800
	global_load_lds_dwordx4 v[8:9], off sc1 nt
	v_lshl_add_u64 v[8:9], v[2:3], 0, s[12:13]
	s_add_i32 m0, s14, 0xe400
	s_mov_b64 s[12:13], 0x5c00
	global_load_lds_dwordx4 v[8:9], off sc1 nt
	v_lshl_add_u64 v[8:9], v[2:3], 0, s[12:13]
	s_add_i32 m0, s14, 0xe800
	s_nop 0
	global_load_lds_dwordx4 v[8:9], off sc1 nt
	s_cbranch_execz .LBB0_2451

; __device__ __forceinline__ void rw2_phase(const Ctx& c0) { const Ctx c = fresh(c0);
;     ...
;         RW2_ISSUE(0); RW2_ISSUE(1); RW2_ISSUE(2); RW2_ISSUE(3);
.LBB0_2445:
	s_mov_b64 s[12:13], 0x6000
	s_lshl_b32 s14, s5, 13
	v_lshl_add_u64 v[6:7], v[2:3], 0, s[12:13]
	s_add_i32 m0, s14, 0x13000
	s_mov_b64 s[12:13], 0x6400
	global_load_lds_dwordx4 v[6:7], off sc1 nt
	v_lshl_add_u64 v[6:7], v[2:3], 0, s[12:13]
	s_add_i32 m0, s14, 0x13400
	s_mov_b64 s[12:13], 0x6800
	global_load_lds_dwordx4 v[6:7], off sc1 nt
	v_lshl_add_u64 v[6:7], v[2:3], 0, s[12:13]
	s_add_i32 m0, s14, 0x13800
	s_mov_b64 s[12:13], 0x6c00
	global_load_lds_dwordx4 v[6:7], off sc1 nt
	v_lshl_add_u64 v[6:7], v[2:3], 0, s[12:13]
	s_add_i32 m0, s14, 0x13c00
	s_mov_b64 s[12:13], 0x7000
	global_load_lds_dwordx4 v[6:7], off sc1 nt
	v_lshl_add_u64 v[6:7], v[2:3], 0, s[12:13]
	s_add_i32 m0, s14, 0x14000
	s_mov_b64 s[12:13], 0x7400
	global_load_lds_dwordx4 v[6:7], off sc1 nt
	v_lshl_add_u64 v[6:7], v[2:3], 0, s[12:13]
	s_add_i32 m0, s14, 0x14400
	s_mov_b64 s[12:13], 0x7800
	global_load_lds_dwordx4 v[6:7], off sc1 nt
	v_lshl_add_u64 v[6:7], v[2:3], 0, s[12:13]
	s_add_i32 m0, s14, 0x14800
	s_mov_b64 s[12:13], 0x7c00
	global_load_lds_dwordx4 v[6:7], off sc1 nt
	v_lshl_add_u64 v[6:7], v[2:3], 0, s[12:13]
	s_add_i32 m0, s14, 0x14c00
	s_nop 0
	global_load_lds_dwordx4 v[6:7], off sc1 nt
	s_cbranch_execz .LBB0_2453

; __device__ __forceinline__ void rw2_phase(const Ctx& c0) { const Ctx c = fresh(c0);
;     ...
;         RW2_ISSUE(0); RW2_ISSUE(1); RW2_ISSUE(2); RW2_ISSUE(3);
.LBB0_2449:
	s_mov_b32 m0, 0xc800
	s_nop 0
	global_load_lds_dwordx4 v[8:9], off sc1 nt
	s_and_b64 vcc, exec, s[0:1]
	s_mov_b64 s[12:13], -1
	s_cbranch_vccz .LBB0_2443

; __device__ __forceinline__ void rw2_phase(const Ctx& c0) { const Ctx c = fresh(c0);
;     ...
;         RW2_ISSUE(0); RW2_ISSUE(1); RW2_ISSUE(2); RW2_ISSUE(3);
.LBB0_2451:
	s_mov_b32 m0, 0x12c00
	s_nop 0
	global_load_lds_dwordx4 v[6:7], off sc1 nt
	s_and_b64 vcc, exec, s[0:1]
	s_mov_b64 s[12:13], -1
	s_cbranch_vccz .LBB0_2445

; __device__ __forceinline__ void rw2_phase(const Ctx& c0) { const Ctx c = fresh(c0);
;     ...
;         RW2_ISSUE(0); RW2_ISSUE(1); RW2_ISSUE(2); RW2_ISSUE(3);
.LBB0_2453:
	s_mov_b32 m0, 0x19000
	s_nop 0
	global_load_lds_dwordx4 v[4:5], off sc1 nt
	s_mov_b64 s[12:13], -1
	s_and_b64 vcc, exec, s[6:7]
	s_cbranch_vccnz .LBB0_2447

; #define RW2_WAIT(k8, k1) do { if (j == 3) asm volatile("s_waitcnt vmcnt(" #k1 ")" ::: "memory"); else asm volatile("s_waitcnt vmcnt(" #k8 ")" ::: "memory"); } while (0)
; __device__ __forceinline__ void rw2_phase(const Ctx& c0) { const Ctx c = fresh(c0);
;     ...
;         for (int n = 0; n < 128; ++n) {
;             if (n + 4 < 128) { RW2_ISSUE(n + 4); RW2_WAIT(24, 3); }
.LBB0_2478:
	s_andn2_b64 vcc, exec, s[8:9]
	s_cbranch_vccnz .LBB0_2457
	s_add_i32 s8, s10, 4
	s_mul_i32 s9, s8, 0xcd
	s_bfe_u32 s9, s9, 0x6000a
	s_mul_i32 s9, s9, 5
	s_sub_i32 s8, s8, s9
	s_and_b32 s11, s8, 0xff
	s_mulk_i32 s11, 0x6400
	s_and_b64 vcc, exec, s[0:1]
	s_mov_b64 s[8:9], -1
	s_cbranch_vccnz .LBB0_2483
	v_lshl_add_u64 v[6:7], v[2:3], 0, s[2:3]
	s_mov_b64 s[8:9], 0x8000
	s_add_i32 s12, s11, s5
	v_lshl_add_u64 v[8:9], v[6:7], 0, s[8:9]
	s_add_i32 m0, s12, 0x400
	s_mov_b64 s[8:9], 0x8400
	global_load_lds_dwordx4 v[8:9], off sc1 nt
	v_lshl_add_u64 v[8:9], v[6:7], 0, s[8:9]
	s_add_i32 m0, s12, 0x800
	s_mov_b64 s[8:9], 0x8800
	global_load_lds_dwordx4 v[8:9], off sc1 nt
	v_lshl_add_u64 v[8:9], v[6:7], 0, s[8:9]
	s_add_i32 m0, s12, 0xc00
	s_mov_b64 s[8:9], 0x8c00
	global_load_lds_dwordx4 v[8:9], off sc1 nt
	v_lshl_add_u64 v[8:9], v[6:7], 0, s[8:9]
	s_add_i32 m0, s12, 0x1000
	s_mov_b64 s[8:9], 0x9000
	global_load_lds_dwordx4 v[8:9], off sc1 nt
	v_lshl_add_u64 v[8:9], v[6:7], 0, s[8:9]
	s_add_i32 m0, s12, 0x1400
	s_mov_b64 s[8:9], 0x9400
	global_load_lds_dwordx4 v[8:9], off sc1 nt
	v_lshl_add_u64 v[8:9], v[6:7], 0, s[8:9]
	s_add_i32 m0, s12, 0x1800
	s_mov_b64 s[8:9], 0x9800
	global_load_lds_dwordx4 v[8:9], off sc1 nt
	v_lshl_add_u64 v[8:9], v[6:7], 0, s[8:9]
	s_add_i32 m0, s12, 0x1c00
	s_mov_b64 s[8:9], 0x9c00
	global_load_lds_dwordx4 v[8:9], off sc1 nt
	v_lshl_add_u64 v[6:7], v[6:7], 0, s[8:9]
	s_add_i32 m0, s12, 0x2000
	s_nop 0
	global_load_lds_dwordx4 v[6:7], off sc1 nt
	s_cbranch_execz .LBB0_2484

; #define RW2_BAR() do { __builtin_amdgcn_s_barrier(); asm volatile("" ::: "memory"); } while (0)
; #define RW2_WAIT(k8, k1) do { if (j == 3) asm volatile("s_waitcnt vmcnt(" #k1 ")" ::: "memory"); else asm volatile("s_waitcnt vmcnt(" #k8 ")" ::: "memory"); } while (0)
; __device__ __forceinline__ void rw2_phase(const Ctx& c0) { const Ctx c = fresh(c0);
;     ...
;         RW2_ISSUE(0); RW2_ISSUE(1); RW2_ISSUE(2); RW2_ISSUE(3);
;         RW2_WAIT(24, 3);
;         RW2_BAR();
;         for (int n = 0; n < 128; ++n) {
;             if (n + 4 < 128) { RW2_ISSUE(n + 4); RW2_WAIT(24, 3); }
.LBB0_2484:
	s_add_i32 m0, s11, 0x6400
	s_nop 0
	global_load_lds_dwordx4 v[4:5], off sc1 nt
	s_mov_b64 s[8:9], -1
	s_and_b64 vcc, exec, s[6:7]
	s_cbranch_vccnz .LBB0_2482
